# code placement: whole instruction stream shifted by 4 bytes (every hot loop head now at offset 0 mod 8 instead of 4 mod 8)
# baseline (speedup 1.0000x reference)
_Z10fwd_kernel4Args:
	s_nop 0
	s_mov_b32 s75, s2
	s_mov_b64 s[2:3], s[0:1]
	s_load_dwordx2 s[36:37], s[2:3], 0xb0
	s_add_u32 s2, s0, 0xc0
	s_addc_u32 s3, s1, 0
	v_readfirstlane_b32 s33, v0
	v_writelane_b32 v252, s2, 0
	s_nop 1
	v_writelane_b32 v252, s3, 1
	s_movk_i32 s2, 0x80
	v_cmp_gt_u32_e32 vcc, s2, v0
	s_and_saveexec_b64 s[2:3], vcc
	v_lshl_add_u32 v1, v0, 2, 0
	v_add_u32_e32 v1, 0x23e00, v1
	v_mov_b32_e32 v2, 0
	ds_write_b32 v1, v2
	s_or_b64 exec, exec, s[2:3]
	s_load_dword s74, s[0:1], 0xc0
	s_waitcnt lgkmcnt(0)
	s_barrier
	s_add_u32 s76, s36, 0x4000
	s_getreg_b32 s2, hwreg(HW_REG_XCC_ID, 0, 4)
	s_addc_u32 s77, s37, 0
	s_and_b32 s78, s2, 15
	v_cmp_eq_u32_e64 s[80:81], 0, v0
	s_and_saveexec_b64 s[2:3], s[80:81]
	s_cbranch_execz .LBB0_5
	s_mov_b64 s[4:5], exec
	v_mbcnt_lo_u32_b32 v0, s4, 0
	v_mbcnt_hi_u32_b32 v0, s5, v0
	v_cmp_eq_u32_e32 vcc, 0, v0
	s_and_b64 s[6:7], exec, vcc
	s_mov_b64 exec, s[6:7]
	s_cbranch_execz .LBB0_5
	s_lshl_b32 s6, s78, 8
	s_bcnt1_i32_b64 s4, s[4:5]
	v_mov_b32_e32 v0, s6
	v_mov_b32_e32 v1, s4
	global_atomic_add v0, v1, s[76:77] offset:1024
